# DSA trims: dead per-group LDS address computations in the P.V loop removed; compaction-loop lane masks copied with s_mov_b64 instead of v_cndmask+v_cmp
# speedup vs baseline: 1.0125x; 1.0125x over previous
.LBB0_236:
	s_waitcnt lgkmcnt(0)
	v_mov_b32_e32 v9, v207
	ds_read_u16 v207, v8 offset:128
	v_cmp_ge_u32_e32 vcc, s50, v5
	v_cmp_lt_u32_sdwa s[28:29], v2, v9 src0_sel:DWORD src1_sel:WORD_0
	s_and_b64 s[90:91], vcc, s[28:29]
	v_cmp_eq_u32_sdwa s[28:29], v2, v9 src0_sel:DWORD src1_sel:WORD_0
	s_and_b64 s[42:43], vcc, s[28:29]
	s_mov_b64 vcc, s[90:91]
	s_mov_b64 s[28:29], s[42:43]
	s_and_saveexec_b64 s[34:35], s[90:91]
	s_cbranch_execz .LBB0_238
	v_and_b32_e32 v10, vcc_lo, v146
	s_lshl_b32 s90, s79, 1
	v_and_b32_e32 v9, vcc_hi, v1
	v_bcnt_u32_b32 v10, v10, 0
	s_add_i32 s90, s78, s90
	v_bcnt_u32_b32 v9, v9, v10
	v_lshl_add_u32 v9, v9, 1, s90
	ds_write_b16 v9, v5

.LBB0_275:
	v_min_i32_e32 v240, s50, v103
	v_lshl_add_u32 v240, v240, 5, v202
	ds_read_b128 v[208:211], v240
	v_add_u32_e32 v241, 4, v103
	v_min_i32_e32 v241, s50, v241
	v_lshl_add_u32 v241, v241, 5, v202
	ds_read_b128 v[212:215], v241
	v_add_u32_e32 v242, 8, v103
	v_min_i32_e32 v242, s50, v242
	v_lshl_add_u32 v242, v242, 5, v202
	ds_read_b128 v[216:219], v242
	v_add_u32_e32 v243, 12, v103
	v_min_i32_e32 v243, s50, v243
	v_lshl_add_u32 v243, v243, 5, v202
	ds_read_b128 v[220:223], v243
	v_add_u32_e32 v244, 16, v103
	v_min_i32_e32 v244, s50, v244
	v_lshl_add_u32 v244, v244, 5, v202
	ds_read_b128 v[224:227], v244
	v_add_u32_e32 v245, 20, v103
	v_min_i32_e32 v245, s50, v245
	v_lshl_add_u32 v245, v245, 5, v202
	ds_read_b128 v[228:231], v245
	v_add_u32_e32 v246, 24, v103
	v_min_i32_e32 v246, s50, v246
	v_lshl_add_u32 v246, v246, 5, v202
	ds_read_b128 v[232:235], v246
	v_add_u32_e32 v247, 28, v103
	v_min_i32_e32 v247, s50, v247
	v_lshl_add_u32 v247, v247, 5, v202
	ds_read_b128 v[236:239], v247
	v_cmp_lt_u32_e32 vcc, s50, v103
	v_lshlrev_b32_e32 v114, 16, v62
	v_and_b32_e32 v115, 0xffff0000, v62
	v_lshlrev_b32_e32 v62, 16, v63
	s_waitcnt lgkmcnt(7)
	v_cndmask_b32_e64 v110, v211, 0, vcc
	v_cndmask_b32_e64 v108, v210, 0, vcc
	v_cndmask_b32_e64 v112, v209, 0, vcc
	v_cndmask_b32_e64 v106, v208, 0, vcc
	v_and_b32_e32 v63, 0xffff0000, v63
	v_pk_fma_f32 v[88:89], v[106:107], v[62:63], v[88:89] op_sel_hi:[0,1,1]
	v_pk_fma_f32 v[86:87], v[112:113], v[62:63], v[86:87] op_sel_hi:[0,1,1]
	v_pk_fma_f32 v[84:85], v[108:109], v[62:63], v[84:85] op_sel_hi:[0,1,1]
	v_pk_fma_f32 v[82:83], v[110:111], v[62:63], v[82:83] op_sel_hi:[0,1,1]
	v_add_u32_e32 v62, 4, v103
	v_cmp_lt_u32_e32 vcc, s50, v62
	v_lshlrev_b32_e32 v116, 16, v64
	v_and_b32_e32 v117, 0xffff0000, v64
	v_lshlrev_b32_e32 v64, 16, v65
	v_and_b32_e32 v65, 0xffff0000, v65
	v_pk_fma_f32 v[72:73], v[106:107], v[64:65], v[72:73] op_sel_hi:[0,1,1]
	v_pk_fma_f32 v[70:71], v[112:113], v[64:65], v[70:71] op_sel_hi:[0,1,1]
	v_pk_fma_f32 v[68:69], v[108:109], v[64:65], v[68:69] op_sel_hi:[0,1,1]
	v_pk_fma_f32 v[66:67], v[110:111], v[64:65], v[66:67] op_sel_hi:[0,1,1]
	v_pk_fma_f32 v[92:93], v[106:107], v[114:115], v[92:93] op_sel_hi:[0,1,1]
	v_pk_fma_f32 v[80:81], v[106:107], v[116:117], v[80:81] op_sel_hi:[0,1,1]
	v_pk_fma_f32 v[94:95], v[108:109], v[114:115], v[94:95] op_sel_hi:[0,1,1]
	v_pk_fma_f32 v[74:75], v[108:109], v[116:117], v[74:75] op_sel_hi:[0,1,1]
	v_pk_fma_f32 v[90:91], v[110:111], v[114:115], v[90:91] op_sel_hi:[0,1,1]
	v_pk_fma_f32 v[76:77], v[110:111], v[116:117], v[76:77] op_sel_hi:[0,1,1]
	s_waitcnt lgkmcnt(6)
	v_cndmask_b32_e64 v106, v215, 0, vcc
	v_cndmask_b32_e64 v64, v214, 0, vcc
	v_cndmask_b32_e64 v108, v213, 0, vcc
	v_cndmask_b32_e64 v62, v212, 0, vcc
	v_lshlrev_b32_e32 v110, 16, v58
	v_and_b32_e32 v111, 0xffff0000, v58
	v_lshlrev_b32_e32 v58, 16, v59
	v_and_b32_e32 v59, 0xffff0000, v59
	v_pk_fma_f32 v[88:89], v[62:63], v[58:59], v[88:89] op_sel_hi:[0,1,1]
	v_pk_fma_f32 v[86:87], v[108:109], v[58:59], v[86:87] op_sel_hi:[0,1,1]
	v_pk_fma_f32 v[84:85], v[64:65], v[58:59], v[84:85] op_sel_hi:[0,1,1]
	v_pk_fma_f32 v[82:83], v[106:107], v[58:59], v[82:83] op_sel_hi:[0,1,1]
	v_add_u32_e32 v58, 8, v103
	v_cmp_lt_u32_e32 vcc, s50, v58
	v_pk_fma_f32 v[96:97], v[112:113], v[114:115], v[96:97] op_sel_hi:[0,1,1]
	v_pk_fma_f32 v[78:79], v[112:113], v[116:117], v[78:79] op_sel_hi:[0,1,1]
	v_lshlrev_b32_e32 v112, 16, v60
	v_and_b32_e32 v113, 0xffff0000, v60
	v_lshlrev_b32_e32 v60, 16, v61
	v_and_b32_e32 v61, 0xffff0000, v61
	v_pk_fma_f32 v[72:73], v[62:63], v[60:61], v[72:73] op_sel_hi:[0,1,1]
	v_pk_fma_f32 v[70:71], v[108:109], v[60:61], v[70:71] op_sel_hi:[0,1,1]
	v_pk_fma_f32 v[68:69], v[64:65], v[60:61], v[68:69] op_sel_hi:[0,1,1]
	v_pk_fma_f32 v[66:67], v[106:107], v[60:61], v[66:67] op_sel_hi:[0,1,1]
	v_pk_fma_f32 v[80:81], v[62:63], v[112:113], v[80:81] op_sel_hi:[0,1,1]
	v_pk_fma_f32 v[62:63], v[62:63], v[110:111], v[92:93] op_sel_hi:[0,1,1]
	v_pk_fma_f32 v[92:93], v[108:109], v[110:111], v[96:97] op_sel_hi:[0,1,1]
	v_pk_fma_f32 v[74:75], v[64:65], v[112:113], v[74:75] op_sel_hi:[0,1,1]
	v_pk_fma_f32 v[64:65], v[64:65], v[110:111], v[94:95] op_sel_hi:[0,1,1]
	v_pk_fma_f32 v[76:77], v[106:107], v[112:113], v[76:77] op_sel_hi:[0,1,1]
	v_pk_fma_f32 v[90:91], v[106:107], v[110:111], v[90:91] op_sel_hi:[0,1,1]
	s_waitcnt lgkmcnt(5)
	v_cndmask_b32_e64 v94, v219, 0, vcc
	v_cndmask_b32_e64 v60, v218, 0, vcc
	v_cndmask_b32_e64 v96, v217, 0, vcc
	v_cndmask_b32_e64 v58, v216, 0, vcc
	v_lshlrev_b32_e32 v106, 16, v54
	v_and_b32_e32 v107, 0xffff0000, v54
	v_lshlrev_b32_e32 v54, 16, v55
	v_and_b32_e32 v55, 0xffff0000, v55
	v_pk_fma_f32 v[88:89], v[58:59], v[54:55], v[88:89] op_sel_hi:[0,1,1]
	v_pk_fma_f32 v[86:87], v[96:97], v[54:55], v[86:87] op_sel_hi:[0,1,1]
	v_pk_fma_f32 v[84:85], v[60:61], v[54:55], v[84:85] op_sel_hi:[0,1,1]
	v_pk_fma_f32 v[82:83], v[94:95], v[54:55], v[82:83] op_sel_hi:[0,1,1]
	v_add_u32_e32 v54, 12, v103
	v_cmp_lt_u32_e32 vcc, s50, v54
	v_pk_fma_f32 v[78:79], v[108:109], v[112:113], v[78:79] op_sel_hi:[0,1,1]
	v_lshlrev_b32_e32 v108, 16, v56
	v_and_b32_e32 v109, 0xffff0000, v56
	v_lshlrev_b32_e32 v56, 16, v57
	v_and_b32_e32 v57, 0xffff0000, v57
	v_pk_fma_f32 v[62:63], v[58:59], v[106:107], v[62:63] op_sel_hi:[0,1,1]
	v_pk_fma_f32 v[80:81], v[58:59], v[108:109], v[80:81] op_sel_hi:[0,1,1]
	v_pk_fma_f32 v[58:59], v[58:59], v[56:57], v[72:73] op_sel_hi:[0,1,1]
	v_pk_fma_f32 v[70:71], v[96:97], v[56:57], v[70:71] op_sel_hi:[0,1,1]
	v_pk_fma_f32 v[64:65], v[60:61], v[106:107], v[64:65] op_sel_hi:[0,1,1]
	v_pk_fma_f32 v[74:75], v[60:61], v[108:109], v[74:75] op_sel_hi:[0,1,1]
	v_pk_fma_f32 v[60:61], v[60:61], v[56:57], v[68:69] op_sel_hi:[0,1,1]
	v_pk_fma_f32 v[66:67], v[94:95], v[56:57], v[66:67] op_sel_hi:[0,1,1]
	v_pk_fma_f32 v[72:73], v[96:97], v[106:107], v[92:93] op_sel_hi:[0,1,1]
	v_pk_fma_f32 v[78:79], v[96:97], v[108:109], v[78:79] op_sel_hi:[0,1,1]
	v_pk_fma_f32 v[68:69], v[94:95], v[106:107], v[90:91] op_sel_hi:[0,1,1]
	v_pk_fma_f32 v[76:77], v[94:95], v[108:109], v[76:77] op_sel_hi:[0,1,1]
	s_waitcnt lgkmcnt(4)
	v_cndmask_b32_e64 v90, v223, 0, vcc
	v_cndmask_b32_e64 v56, v222, 0, vcc
	v_cndmask_b32_e64 v92, v221, 0, vcc
	v_cndmask_b32_e64 v54, v220, 0, vcc
	v_lshlrev_b32_e32 v94, 16, v50
	v_and_b32_e32 v95, 0xffff0000, v50
	v_lshlrev_b32_e32 v50, 16, v51
	v_and_b32_e32 v51, 0xffff0000, v51
	v_lshlrev_b32_e32 v96, 16, v52
	v_and_b32_e32 v97, 0xffff0000, v52
	v_lshlrev_b32_e32 v52, 16, v53
	v_and_b32_e32 v53, 0xffff0000, v53
	v_pk_fma_f32 v[58:59], v[54:55], v[52:53], v[58:59] op_sel_hi:[0,1,1]
	v_pk_fma_f32 v[80:81], v[54:55], v[96:97], v[80:81] op_sel_hi:[0,1,1]
	v_pk_fma_f32 v[88:89], v[54:55], v[50:51], v[88:89] op_sel_hi:[0,1,1]
	v_pk_fma_f32 v[54:55], v[54:55], v[94:95], v[62:63] op_sel_hi:[0,1,1]
	v_pk_fma_f32 v[62:63], v[92:93], v[52:53], v[70:71] op_sel_hi:[0,1,1]
	v_pk_fma_f32 v[70:71], v[92:93], v[96:97], v[78:79] op_sel_hi:[0,1,1]
	v_pk_fma_f32 v[78:79], v[92:93], v[50:51], v[86:87] op_sel_hi:[0,1,1]
	v_pk_fma_f32 v[60:61], v[56:57], v[52:53], v[60:61] op_sel_hi:[0,1,1]
	v_pk_fma_f32 v[74:75], v[56:57], v[96:97], v[74:75] op_sel_hi:[0,1,1]
	v_pk_fma_f32 v[84:85], v[56:57], v[50:51], v[84:85] op_sel_hi:[0,1,1]
	v_pk_fma_f32 v[56:57], v[56:57], v[94:95], v[64:65] op_sel_hi:[0,1,1]
	v_pk_fma_f32 v[64:65], v[90:91], v[52:53], v[66:67] op_sel_hi:[0,1,1]
	v_pk_fma_f32 v[66:67], v[90:91], v[96:97], v[76:77] op_sel_hi:[0,1,1]
	v_pk_fma_f32 v[76:77], v[90:91], v[50:51], v[82:83] op_sel_hi:[0,1,1]
	v_add_u32_e32 v50, 16, v103
	v_cmp_lt_u32_e32 vcc, s50, v50
	v_pk_fma_f32 v[72:73], v[92:93], v[94:95], v[72:73] op_sel_hi:[0,1,1]
	v_pk_fma_f32 v[68:69], v[90:91], v[94:95], v[68:69] op_sel_hi:[0,1,1]
	v_lshlrev_b32_e32 v90, 16, v46
	v_and_b32_e32 v91, 0xffff0000, v46
	s_waitcnt lgkmcnt(3)
	v_cndmask_b32_e64 v82, v227, 0, vcc
	v_cndmask_b32_e64 v52, v226, 0, vcc
	v_cndmask_b32_e64 v86, v225, 0, vcc
	v_cndmask_b32_e64 v50, v224, 0, vcc
	v_lshlrev_b32_e32 v46, 16, v47
	v_and_b32_e32 v47, 0xffff0000, v47
	v_lshlrev_b32_e32 v92, 16, v48
	v_and_b32_e32 v93, 0xffff0000, v48
	v_lshlrev_b32_e32 v48, 16, v49
	v_and_b32_e32 v49, 0xffff0000, v49
	v_pk_fma_f32 v[54:55], v[50:51], v[90:91], v[54:55] op_sel_hi:[0,1,1]
	v_pk_fma_f32 v[88:89], v[50:51], v[46:47], v[88:89] op_sel_hi:[0,1,1]
	v_pk_fma_f32 v[80:81], v[50:51], v[92:93], v[80:81] op_sel_hi:[0,1,1]
	v_pk_fma_f32 v[50:51], v[50:51], v[48:49], v[58:59] op_sel_hi:[0,1,1]
	v_pk_fma_f32 v[58:59], v[86:87], v[90:91], v[72:73] op_sel_hi:[0,1,1]
	v_pk_fma_f32 v[72:73], v[86:87], v[46:47], v[78:79] op_sel_hi:[0,1,1]
	v_pk_fma_f32 v[56:57], v[52:53], v[90:91], v[56:57] op_sel_hi:[0,1,1]
	v_pk_fma_f32 v[78:79], v[52:53], v[46:47], v[84:85] op_sel_hi:[0,1,1]
	v_pk_fma_f32 v[74:75], v[52:53], v[92:93], v[74:75] op_sel_hi:[0,1,1]
	v_pk_fma_f32 v[52:53], v[52:53], v[48:49], v[60:61] op_sel_hi:[0,1,1]
	v_pk_fma_f32 v[60:61], v[82:83], v[90:91], v[68:69] op_sel_hi:[0,1,1]
	v_pk_fma_f32 v[68:69], v[82:83], v[46:47], v[76:77] op_sel_hi:[0,1,1]
	v_add_u32_e32 v46, 20, v103
	v_cmp_lt_u32_e32 vcc, s50, v46
	v_pk_fma_f32 v[62:63], v[86:87], v[48:49], v[62:63] op_sel_hi:[0,1,1]
	v_pk_fma_f32 v[64:65], v[82:83], v[48:49], v[64:65] op_sel_hi:[0,1,1]
	v_pk_fma_f32 v[70:71], v[86:87], v[92:93], v[70:71] op_sel_hi:[0,1,1]
	v_pk_fma_f32 v[66:67], v[82:83], v[92:93], v[66:67] op_sel_hi:[0,1,1]
	v_lshlrev_b32_e32 v84, 16, v10
	v_and_b32_e32 v85, 0xffff0000, v10
	s_waitcnt lgkmcnt(2)
	v_cndmask_b32_e64 v76, v231, 0, vcc
	v_cndmask_b32_e64 v48, v230, 0, vcc
	v_cndmask_b32_e64 v82, v229, 0, vcc
	v_cndmask_b32_e64 v46, v228, 0, vcc
	v_lshlrev_b32_e32 v10, 16, v11
	v_and_b32_e32 v11, 0xffff0000, v11
	v_lshlrev_b32_e32 v86, 16, v12
	v_and_b32_e32 v87, 0xffff0000, v12
	v_lshlrev_b32_e32 v12, 16, v13
	v_and_b32_e32 v13, 0xffff0000, v13
	v_pk_fma_f32 v[50:51], v[46:47], v[12:13], v[50:51] op_sel_hi:[0,1,1]
	v_pk_fma_f32 v[80:81], v[46:47], v[86:87], v[80:81] op_sel_hi:[0,1,1]
	v_pk_fma_f32 v[88:89], v[46:47], v[10:11], v[88:89] op_sel_hi:[0,1,1]
	v_pk_fma_f32 v[46:47], v[46:47], v[84:85], v[54:55] op_sel_hi:[0,1,1]
	v_pk_fma_f32 v[54:55], v[82:83], v[12:13], v[62:63] op_sel_hi:[0,1,1]
	v_pk_fma_f32 v[62:63], v[82:83], v[86:87], v[70:71] op_sel_hi:[0,1,1]
	v_pk_fma_f32 v[70:71], v[82:83], v[10:11], v[72:73] op_sel_hi:[0,1,1]
	v_pk_fma_f32 v[52:53], v[48:49], v[12:13], v[52:53] op_sel_hi:[0,1,1]
	v_pk_fma_f32 v[72:73], v[48:49], v[86:87], v[74:75] op_sel_hi:[0,1,1]
	v_pk_fma_f32 v[74:75], v[48:49], v[10:11], v[78:79] op_sel_hi:[0,1,1]
	v_pk_fma_f32 v[48:49], v[48:49], v[84:85], v[56:57] op_sel_hi:[0,1,1]
	v_pk_fma_f32 v[56:57], v[76:77], v[12:13], v[64:65] op_sel_hi:[0,1,1]
	v_pk_fma_f32 v[64:65], v[76:77], v[86:87], v[66:67] op_sel_hi:[0,1,1]
	v_pk_fma_f32 v[66:67], v[76:77], v[10:11], v[68:69] op_sel_hi:[0,1,1]
	v_add_u32_e32 v10, 24, v103
	v_cmp_lt_u32_e32 vcc, s50, v10
	v_pk_fma_f32 v[58:59], v[82:83], v[84:85], v[58:59] op_sel_hi:[0,1,1]
	v_pk_fma_f32 v[60:61], v[76:77], v[84:85], v[60:61] op_sel_hi:[0,1,1]
	v_lshlrev_b32_e32 v78, 16, v6
	v_and_b32_e32 v79, 0xffff0000, v6
	s_waitcnt lgkmcnt(1)
	v_cndmask_b32_e64 v68, v235, 0, vcc
	v_cndmask_b32_e64 v12, v234, 0, vcc
	v_cndmask_b32_e64 v76, v233, 0, vcc
	v_cndmask_b32_e64 v10, v232, 0, vcc
	v_lshlrev_b32_e32 v6, 16, v7
	v_and_b32_e32 v7, 0xffff0000, v7
	v_lshlrev_b32_e32 v82, 16, v8
	v_and_b32_e32 v83, 0xffff0000, v8
	v_lshlrev_b32_e32 v8, 16, v9
	v_and_b32_e32 v9, 0xffff0000, v9
	v_pk_fma_f32 v[46:47], v[10:11], v[78:79], v[46:47] op_sel_hi:[0,1,1]
	v_pk_fma_f32 v[84:85], v[10:11], v[6:7], v[88:89] op_sel_hi:[0,1,1]
	v_pk_fma_f32 v[80:81], v[10:11], v[82:83], v[80:81] op_sel_hi:[0,1,1]
	v_pk_fma_f32 v[10:11], v[10:11], v[8:9], v[50:51] op_sel_hi:[0,1,1]
	v_pk_fma_f32 v[50:51], v[76:77], v[78:79], v[58:59] op_sel_hi:[0,1,1]
	v_pk_fma_f32 v[58:59], v[76:77], v[6:7], v[70:71] op_sel_hi:[0,1,1]
	v_pk_fma_f32 v[62:63], v[76:77], v[82:83], v[62:63] op_sel_hi:[0,1,1]
	v_pk_fma_f32 v[54:55], v[76:77], v[8:9], v[54:55] op_sel_hi:[0,1,1]
	v_pk_fma_f32 v[48:49], v[12:13], v[78:79], v[48:49] op_sel_hi:[0,1,1]
	v_pk_fma_f32 v[76:77], v[12:13], v[6:7], v[74:75] op_sel_hi:[0,1,1]
	v_pk_fma_f32 v[74:75], v[12:13], v[82:83], v[72:73] op_sel_hi:[0,1,1]
	v_pk_fma_f32 v[12:13], v[12:13], v[8:9], v[52:53] op_sel_hi:[0,1,1]
	v_pk_fma_f32 v[52:53], v[68:69], v[78:79], v[60:61] op_sel_hi:[0,1,1]
	v_pk_fma_f32 v[60:61], v[68:69], v[6:7], v[66:67] op_sel_hi:[0,1,1]
	v_add_u32_e32 v6, 28, v103
	v_cmp_lt_u32_e32 vcc, s50, v6
	v_pk_fma_f32 v[56:57], v[68:69], v[8:9], v[56:57] op_sel_hi:[0,1,1]
	v_pk_fma_f32 v[64:65], v[68:69], v[82:83], v[64:65] op_sel_hi:[0,1,1]
	v_lshlrev_b32_e32 v106, 16, v2
	v_and_b32_e32 v107, 0xffff0000, v2
	v_lshlrev_b32_e32 v2, 16, v3
	s_waitcnt lgkmcnt(0)
	v_cndmask_b32_e64 v90, v239, 0, vcc
	v_cndmask_b32_e64 v8, v238, 0, vcc
	v_cndmask_b32_e64 v66, v237, 0, vcc
	v_cndmask_b32_e64 v6, v236, 0, vcc
	v_and_b32_e32 v3, 0xffff0000, v3
	v_lshlrev_b32_e32 v82, 16, v4
	v_and_b32_e32 v83, 0xffff0000, v4
	v_lshlrev_b32_e32 v4, 16, v5
	v_and_b32_e32 v5, 0xffff0000, v5
	v_pk_fma_f32 v[72:73], v[6:7], v[4:5], v[10:11] op_sel_hi:[0,1,1]
	v_pk_fma_f32 v[80:81], v[6:7], v[82:83], v[80:81] op_sel_hi:[0,1,1]
	v_pk_fma_f32 v[88:89], v[6:7], v[2:3], v[84:85] op_sel_hi:[0,1,1]
	v_pk_fma_f32 v[92:93], v[6:7], v[106:107], v[46:47] op_sel_hi:[0,1,1]
	v_pk_fma_f32 v[70:71], v[66:67], v[4:5], v[54:55] op_sel_hi:[0,1,1]
	v_pk_fma_f32 v[78:79], v[66:67], v[82:83], v[62:63] op_sel_hi:[0,1,1]
	v_pk_fma_f32 v[86:87], v[66:67], v[2:3], v[58:59] op_sel_hi:[0,1,1]
	v_pk_fma_f32 v[96:97], v[66:67], v[106:107], v[50:51] op_sel_hi:[0,1,1]
	v_pk_fma_f32 v[68:69], v[8:9], v[4:5], v[12:13] op_sel_hi:[0,1,1]
	v_pk_fma_f32 v[74:75], v[8:9], v[82:83], v[74:75] op_sel_hi:[0,1,1]
	v_pk_fma_f32 v[84:85], v[8:9], v[2:3], v[76:77] op_sel_hi:[0,1,1]
	v_pk_fma_f32 v[94:95], v[8:9], v[106:107], v[48:49] op_sel_hi:[0,1,1]
	v_pk_fma_f32 v[66:67], v[90:91], v[4:5], v[56:57] op_sel_hi:[0,1,1]
	v_pk_fma_f32 v[76:77], v[90:91], v[82:83], v[64:65] op_sel_hi:[0,1,1]
	v_pk_fma_f32 v[82:83], v[90:91], v[2:3], v[60:61] op_sel_hi:[0,1,1]
	v_pk_fma_f32 v[90:91], v[90:91], v[106:107], v[52:53] op_sel_hi:[0,1,1]
	s_add_i32 s76, s76, 8
	s_andn2_b64 vcc, exec, s[34:35]
	v_mov_b32_e32 v103, v104
	s_waitcnt vmcnt(0)
	v_mov_b64_e32 v[2:3], v[42:43]
	v_mov_b64_e32 v[4:5], v[44:45]
	v_mov_b64_e32 v[6:7], v[38:39]
	v_mov_b64_e32 v[8:9], v[40:41]
	v_mov_b64_e32 v[10:11], v[34:35]
	v_mov_b64_e32 v[12:13], v[36:37]
	v_mov_b64_e32 v[46:47], v[30:31]
	v_mov_b64_e32 v[48:49], v[32:33]
	v_mov_b64_e32 v[50:51], v[26:27]
	v_mov_b64_e32 v[52:53], v[28:29]
	v_mov_b64_e32 v[54:55], v[22:23]
	v_mov_b64_e32 v[56:57], v[24:25]
	v_mov_b64_e32 v[58:59], v[18:19]
	v_mov_b64_e32 v[60:61], v[20:21]
	v_mov_b64_e32 v[62:63], v[14:15]
	v_mov_b64_e32 v[64:65], v[16:17]
	s_cbranch_vccz .LBB0_241
